# MLA: K/V LDS writes + tile barrier moved before the PV MFMAs, next-tile first K fragments read right after the barrier (hidden under PV)
# baseline (speedup 1.0000x reference)
.LBB0_1370:
	v_exp_f32_e32 v96, v96
	v_exp_f32_e32 v97, v97
	v_exp_f32_e32 v98, v98
	v_exp_f32_e32 v99, v99
	v_exp_f32_e32 v100, v100
	v_exp_f32_e32 v101, v101
	v_exp_f32_e32 v102, v102
	v_exp_f32_e32 v103, v103
	v_cvt_pk_bf16_f32 v96, v96, v97
	v_cvt_pk_bf16_f32 v97, v98, v99
	v_cvt_pk_bf16_f32 v98, v100, v101
	v_cvt_pk_bf16_f32 v99, v102, v103
	v_exp_f32_e32 v88, v88
	v_exp_f32_e32 v89, v89
	v_exp_f32_e32 v90, v90
	v_exp_f32_e32 v91, v91
	v_exp_f32_e32 v100, v92
	v_exp_f32_e32 v101, v93
	v_exp_f32_e32 v102, v94
	v_exp_f32_e32 v103, v95
	v_mov_b64_e32 v[136:137], s[14:15]
	v_mov_b64_e32 v[134:135], s[12:13]
	v_mov_b32_e32 v109, v108
	v_mov_b32_e32 v110, v108
	v_mov_b32_e32 v111, v108
	s_waitcnt lgkmcnt(1)
	v_mov_b32_e32 v105, v104
	v_mov_b32_e32 v106, v104
	s_waitcnt lgkmcnt(0)
	v_mov_b32_e32 v107, v104
	v_cvt_pk_bf16_f32 v88, v88, v89
	v_cvt_pk_bf16_f32 v89, v90, v91
	v_cvt_pk_bf16_f32 v90, v100, v101
	v_cvt_pk_bf16_f32 v91, v102, v103
	v_mfma_f32_16x16x32_bf16 v[100:103], v[68:71], v[96:99], v[108:111]
	v_exp_f32_e32 v113, v76
	v_exp_f32_e32 v115, v81
	v_exp_f32_e32 v117, v82
	v_mfma_f32_16x16x32_bf16 v[122:125], v[68:71], v[88:91], v[104:107]
	v_exp_f32_e32 v68, v77
	v_exp_f32_e32 v69, v78
	v_exp_f32_e32 v70, v79
	v_mfma_f32_16x16x32_bf16 v[76:79], v[64:67], v[96:99], v[108:111]
	v_exp_f32_e32 v71, v80
	v_cvt_pk_bf16_f32 v80, v113, v68
	v_cvt_pk_bf16_f32 v81, v69, v70
	v_mfma_f32_16x16x32_bf16 v[126:129], v[64:67], v[88:91], v[104:107]
	v_exp_f32_e32 v64, v83
	v_cvt_pk_bf16_f32 v82, v71, v115
	s_waitcnt vmcnt(1)
	ds_write_b128 v121, v[32:35] offset:14336
	v_mfma_f32_16x16x32_bf16 v[130:133], v[52:55], v[96:99], v[108:111]
	v_cvt_pk_bf16_f32 v83, v117, v64
	v_lshlrev_b32_e32 v144, 1, v116
	v_mfma_f32_16x16x32_bf16 v[138:141], v[52:55], v[88:91], v[104:107]
	v_exp_f32_e32 v52, v56
	v_exp_f32_e32 v53, v57
	v_exp_f32_e32 v54, v58
	v_exp_f32_e32 v55, v59
	v_exp_f32_e32 v56, v60
	v_exp_f32_e32 v57, v61
	v_exp_f32_e32 v58, v62
	v_exp_f32_e32 v59, v63
	v_mfma_f32_16x16x32_bf16 v[92:95], v[84:87], v[96:99], v[108:111]
	v_mfma_f32_16x16x32_bf16 v[84:87], v[84:87], v[88:91], v[104:107]
	v_mfma_f32_16x16x32_bf16 v[96:99], v[134:137], v[96:99], v[108:111]
	v_mfma_f32_16x16x32_bf16 v[88:91], v[134:137], v[88:91], v[104:107]
	s_nop 2
	v_cvt_pk_bf16_f32 v104, v52, v53
	v_cvt_pk_bf16_f32 v105, v54, v55
	v_cvt_pk_bf16_f32 v106, v56, v57
	v_cvt_pk_bf16_f32 v107, v58, v59
	v_mfma_f32_16x16x32_bf16 v[68:71], v[48:51], v[80:83], v[92:95]
	s_nop 0
	v_mfma_f32_16x16x32_bf16 v[64:67], v[48:51], v[104:107], v[84:87]
	v_mfma_f32_16x16x32_bf16 v[60:63], v[44:47], v[80:83], v[100:103]
	v_mfma_f32_16x16x32_bf16 v[56:59], v[44:47], v[104:107], v[122:125]
	v_mfma_f32_16x16x32_bf16 v[52:55], v[40:43], v[80:83], v[76:79]
	v_mfma_f32_16x16x32_bf16 v[48:51], v[40:43], v[104:107], v[126:129]
	v_mfma_f32_16x16x32_bf16 v[44:47], v[36:39], v[80:83], v[130:133]
	v_mfma_f32_16x16x32_bf16 v[40:43], v[36:39], v[104:107], v[138:141]
	v_mfma_f32_16x16x32_bf16 v[36:39], v[134:137], v[80:83], v[96:99]
	v_mfma_f32_16x16x32_bf16 v[32:35], v[134:137], v[104:107], v[88:91]
	s_and_saveexec_b64 s[26:27], s[6:7]
	v_lshl_add_u32 v76, v171, 1, v144
	ds_write_b128 v76, v[28:31] offset:14336
	s_or_b64 exec, exec, s[26:27]
	s_lshl_b32 s26, s43, 8
	v_mov_b32_e32 v115, v145
	s_addk_i32 s26, 0x7800
	s_mov_b32 s27, 1
	v_lshl_add_u64 v[160:161], s[0:1], 0, v[114:115]
	v_add_u32_e32 v177, 0x80, v119
	v_add_u32_e32 v178, 0x80, v120
	v_add_u32_e32 v179, 0x80, v118
	v_lshlrev_b32_e32 v180, 1, v112
	v_mov_b32_e32 v203, 0
	v_mov_b32_e32 v210, v179
	v_mov_b32_e32 v211, 0
	v_mov_b32_e32 v214, 0x800
	v_lshlrev_b64 v[212:213], 11, v[210:211]
	v_lshlrev_b64 v[210:211], 6, v[210:211]
	v_lshl_add_u64 v[210:211], v[152:153], 0, v[210:211]
	v_lshl_add_u64 v[212:213], v[150:151], 0, v[212:213]
	v_lshl_add_u64 v[210:211], v[210:211], 0, s[24:25]
	v_cndmask_b32_e64 v205, v211, v213, s[4:5]
	v_cndmask_b32_e64 v204, v210, v212, s[4:5]
	v_mov_b32_e32 v206, 64
	v_cndmask_b32_e64 v206, v206, v214, s[4:5]
	v_mov_b32_e32 v210, v177
	v_mov_b32_e32 v211, 0
	v_lshlrev_b64 v[212:213], 11, v[210:211]
	v_lshlrev_b64 v[210:211], 6, v[210:211]
	v_lshl_add_u64 v[212:213], v[156:157], 0, v[212:213]
	v_lshl_add_u64 v[210:211], v[154:155], 0, v[210:211]
	v_cndmask_b32_e64 v209, v211, v213, s[8:9]
	v_cndmask_b32_e64 v208, v210, v212, s[8:9]
	v_mov_b32_e32 v207, 64
	v_cndmask_b32_e64 v207, v207, v214, s[8:9]
	v_mov_b32_e32 v210, v178
	v_mov_b32_e32 v211, 0
	v_lshlrev_b64 v[210:211], 11, v[210:211]
	v_lshl_add_u64 v[216:217], v[160:161], 0, v[210:211]
	v_xor_b32_e32 v218, 0x80000000, v159
	v_xor_b32_e32 v222, 0x80000000, v158
	v_mov_b32_e32 v219, v218
	v_mov_b32_e32 v220, v218
	v_mov_b32_e32 v221, v218
	v_mov_b32_e32 v223, v222
	v_mov_b32_e32 v224, v222
	v_mov_b32_e32 v225, v222
	v_mov_b64_e32 v[228:229], s[12:13]
	v_mov_b64_e32 v[230:231], s[14:15]
	s_waitcnt vmcnt(0)
	ds_write_b128 v174, v[72:75] offset:38912
	s_waitcnt lgkmcnt(0)
	s_barrier
	v_add_u32_e32 v244, 0x3800, v175
	ds_read_b128 v[236:239], v244
	ds_read_b128 v[240:243], v244 offset:64
	s_branch .LBB0_1374
.LBB0_1374:
	s_and_b32 s99, s27, 1
	s_mul_i32 s99, s99, 0x3800
	v_add_u32_e32 v124, s99, v175
	s_cmp_lt_u32 s27, 31
	s_cselect_b32 s43, s42, s26
	s_lshl_b32 s98, s27, 6
	s_add_i32 s98, s98, s43
	s_addk_i32 s98, 0xffc0
	s_lshl_b32 s100, s98, 11
	s_mov_b32 s101, 0
	v_mul_u32_u24_e32 v202, s98, v206
	v_lshl_add_u64 v[72:73], v[204:205], 0, v[202:203]
	global_load_dwordx4 v[72:75], v[72:73], off
	s_and_saveexec_b64 s[0:1], s[6:7]
	s_cbranch_execz .LBB0_1376
	v_mul_u32_u24_e32 v202, s98, v207
	v_lshl_add_u64 v[28:29], v[208:209], 0, v[202:203]
	global_load_dwordx4 v[28:31], v[28:29], off
.LBB0_1376:
	s_or_b64 exec, exec, s[0:1]
	v_lshl_add_u64 v[232:233], v[216:217], 0, s[100:101]
	global_load_dwordx4 v[232:235], v[232:233], off offset:128
	s_and_b32 s0, s27, 1
	s_mul_i32 s1, s0, 0x3800
	s_waitcnt lgkmcnt(1)
	v_mfma_f32_16x16x32_bf16 v[92:95], v[236:239], v[20:23], v[218:221]
	ds_read_b128 v[96:99], v124 offset:3584
	ds_read_b128 v[100:103], v124 offset:128
	ds_read_b128 v[108:111], v124 offset:7168
	ds_read_b128 v[112:115], v124 offset:7232
	ds_read_b128 v[120:123], v124 offset:10752
	ds_read_b128 v[182:185], v124 offset:7296
	v_mfma_f32_16x16x32_bf16 v[76:79], v[236:239], v[24:27], v[222:225]
	s_mul_i32 s1, s0, 0x2800
	s_waitcnt lgkmcnt(5)
	v_mfma_f32_16x16x32_bf16 v[104:107], v[96:99], v[20:23], v[218:221]
	v_mfma_f32_16x16x32_bf16 v[96:99], v[96:99], v[24:27], v[222:225]
	s_waitcnt lgkmcnt(3)
	v_mfma_f32_16x16x32_bf16 v[116:119], v[108:111], v[20:23], v[218:221]
	v_mfma_f32_16x16x32_bf16 v[108:111], v[108:111], v[24:27], v[222:225]
	s_waitcnt lgkmcnt(1)
	v_mfma_f32_16x16x32_bf16 v[80:83], v[120:123], v[20:23], v[218:221]
	v_mfma_f32_16x16x32_bf16 v[84:87], v[120:123], v[24:27], v[222:225]
	v_mfma_f32_16x16x32_bf16 v[92:95], v[240:243], v[12:15], v[92:95]
	v_mfma_f32_16x16x32_bf16 v[76:79], v[240:243], v[16:19], v[76:79]
	ds_read_b128 v[88:91], v124 offset:3648
	ds_read_b128 v[120:123], v124 offset:3712
	s_waitcnt lgkmcnt(1)
	v_mfma_f32_16x16x32_bf16 v[104:107], v[88:91], v[12:15], v[104:107]
	v_mfma_f32_16x16x32_bf16 v[88:91], v[88:91], v[16:19], v[96:99]
	s_nop 2
	ds_read_b128 v[96:99], v124 offset:10816
	ds_read_b128 v[190:193], v124 offset:10880
	s_waitcnt lgkmcnt(1)
	v_mfma_f32_16x16x32_bf16 v[194:197], v[96:99], v[12:15], v[80:83]
	s_nop 2
	v_mfma_f32_16x16x32_bf16 v[128:131], v[100:103], v[4:7], v[76:79]
	v_add_u32_e32 v82, s1, v176
	s_nop 1
	v_mfma_f32_16x16x32_bf16 v[116:119], v[112:115], v[12:15], v[116:119]
	v_mfma_f32_16x16x32_bf16 v[186:189], v[112:115], v[16:19], v[108:111]
	v_mfma_f32_16x16x32_bf16 v[198:201], v[96:99], v[16:19], v[84:87]
	ds_read_b64_tr_b16 v[124:125], v82 offset:28672
	ds_read_b64_tr_b16 v[112:113], v82 offset:28704
	ds_read_b64_tr_b16 v[108:109], v82 offset:28736
	ds_read_b64_tr_b16 v[96:97], v82 offset:28768
	ds_read_b64_tr_b16 v[126:127], v82 offset:31232
	ds_read_b64_tr_b16 v[114:115], v82 offset:31264
	ds_read_b64_tr_b16 v[110:111], v82 offset:31296
	ds_read_b64_tr_b16 v[98:99], v82 offset:31328
	v_mfma_f32_16x16x32_bf16 v[136:139], v[100:103], v[8:11], v[92:95]
	v_mfma_f32_16x16x32_bf16 v[132:135], v[120:123], v[4:7], v[88:91]
	s_nop 1
	ds_read_b64_tr_b16 v[92:93], v82 offset:33792
	ds_read_b64_tr_b16 v[88:89], v82 offset:33824
	ds_read_b64_tr_b16 v[84:85], v82 offset:33856
	ds_read_b64_tr_b16 v[80:81], v82 offset:33888
	ds_read_b64_tr_b16 v[94:95], v82 offset:36352
	ds_read_b64_tr_b16 v[90:91], v82 offset:36384
	ds_read_b64_tr_b16 v[86:87], v82 offset:36416
	ds_read_b64_tr_b16 v[82:83], v82 offset:36448
	v_mfma_f32_16x16x32_bf16 v[140:143], v[120:123], v[8:11], v[104:107]
	v_mfma_f32_16x16x32_bf16 v[116:119], v[182:185], v[8:11], v[116:119]
	v_mfma_f32_16x16x32_bf16 v[100:103], v[182:185], v[4:7], v[186:189]
	s_waitcnt lgkmcnt(14)
	v_mfma_f32_16x16x32_bf16 v[120:123], v[190:193], v[8:11], v[194:197]
	v_mfma_f32_16x16x32_bf16 v[104:107], v[190:193], v[4:7], v[198:201]
	v_max3_f32 v181, v136, v137, v138
	v_max3_f32 v183, v128, v129, v130
	v_max3_f32 v184, v131, v132, v133
	v_max3_f32 v181, v181, v139, v140
	v_max3_f32 v183, v183, v134, v135
	v_max3_f32 v181, v181, v141, v142
	v_max3_f32 v182, v143, v116, v117
	v_max3_f32 v184, v184, v100, v101
	v_max3_f32 v182, v182, v118, v119
	v_max3_f32 v184, v184, v102, v103
	v_max3_f32 v181, v181, v120, v121
	v_max3_f32 v182, v182, v122, v123
	v_max3_f32 v183, v183, v104, v105
	v_max3_f32 v184, v184, v106, v107
	v_max_f32_e32 v181, v181, v182
	v_max_f32_e32 v183, v183, v184
	v_max_f32_e32 v184, v181, v183
	v_cmp_lt_f32_e32 vcc, s36, v184
	s_cbranch_vccz .LBB0_1378
	v_mov_b32_e32 v182, v181
	v_mov_b32_e32 v184, v183
	s_nop 1
	v_permlane16_swap_b32_e32 v181, v182
	v_permlane16_swap_b32_e32 v183, v184
	v_max_f32_e32 v181, v181, v182
	v_max_f32_e32 v183, v183, v184
	v_mov_b32_e32 v182, v181
	v_mov_b32_e32 v184, v183
	s_nop 1
	v_permlane32_swap_b32_e32 v181, v182
	v_permlane32_swap_b32_e32 v183, v184
	v_max_f32_e32 v182, v181, v182
	v_max_f32_e32 v181, v183, v184
	v_max_f32_e32 v182, v182, v182
	v_max_f32_e32 v183, 0, v182
	v_exp_f32_e64 v182, -v183
	v_max_f32_e32 v181, v181, v181
	v_sub_f32_e32 v136, v136, v183
	v_sub_f32_e32 v137, v137, v183
	v_pk_mul_f32 v[70:71], v[70:71], v[182:183] op_sel_hi:[1,0]
	v_pk_mul_f32 v[68:69], v[68:69], v[182:183] op_sel_hi:[1,0]
	v_pk_mul_f32 v[62:63], v[62:63], v[182:183] op_sel_hi:[1,0]
	v_pk_mul_f32 v[60:61], v[60:61], v[182:183] op_sel_hi:[1,0]
	v_pk_mul_f32 v[54:55], v[54:55], v[182:183] op_sel_hi:[1,0]
	v_pk_mul_f32 v[52:53], v[52:53], v[182:183] op_sel_hi:[1,0]
	v_pk_mul_f32 v[46:47], v[46:47], v[182:183] op_sel_hi:[1,0]
	v_pk_mul_f32 v[44:45], v[44:45], v[182:183] op_sel_hi:[1,0]
	v_pk_mul_f32 v[38:39], v[38:39], v[182:183] op_sel_hi:[1,0]
	v_pk_mul_f32 v[36:37], v[36:37], v[182:183] op_sel_hi:[1,0]
	v_max_f32_e32 v182, 0, v181
	v_exp_f32_e64 v184, -v182
	v_sub_f32_e32 v138, v138, v183
	v_sub_f32_e32 v139, v139, v183
	v_sub_f32_e32 v140, v140, v183
	v_sub_f32_e32 v141, v141, v183
	v_sub_f32_e32 v142, v142, v183
	v_sub_f32_e32 v143, v143, v183
	v_sub_f32_e32 v116, v116, v183
	v_sub_f32_e32 v117, v117, v183
	v_sub_f32_e32 v118, v118, v183
	v_sub_f32_e32 v119, v119, v183
	v_sub_f32_e32 v120, v120, v183
	v_sub_f32_e32 v121, v121, v183
	v_sub_f32_e32 v122, v122, v183
	v_sub_f32_e32 v123, v123, v183
	v_pk_add_f32 v[158:159], v[158:159], v[182:183]
	v_xor_b32_e32 v218, 0x80000000, v159
	v_xor_b32_e32 v222, 0x80000000, v158
	v_mov_b32_e32 v219, v218
	v_mov_b32_e32 v220, v218
	v_mov_b32_e32 v221, v218
	v_mov_b32_e32 v223, v222
	v_mov_b32_e32 v224, v222
	v_mov_b32_e32 v225, v222
	v_sub_f32_e32 v128, v128, v182
	v_sub_f32_e32 v129, v129, v182
	v_sub_f32_e32 v130, v130, v182
	v_sub_f32_e32 v131, v131, v182
	v_sub_f32_e32 v132, v132, v182
	v_sub_f32_e32 v133, v133, v182
	v_sub_f32_e32 v134, v134, v182
	v_sub_f32_e32 v135, v135, v182
	v_sub_f32_e32 v100, v100, v182
	v_sub_f32_e32 v101, v101, v182
	v_sub_f32_e32 v102, v102, v182
	v_sub_f32_e32 v103, v103, v182
	v_sub_f32_e32 v104, v104, v182
	v_sub_f32_e32 v105, v105, v182
	v_sub_f32_e32 v106, v106, v182
	v_sub_f32_e32 v107, v107, v182
	v_pk_mul_f32 v[66:67], v[66:67], v[184:185] op_sel_hi:[1,0]
	v_pk_mul_f32 v[64:65], v[64:65], v[184:185] op_sel_hi:[1,0]
	v_pk_mul_f32 v[58:59], v[58:59], v[184:185] op_sel_hi:[1,0]
	v_pk_mul_f32 v[56:57], v[56:57], v[184:185] op_sel_hi:[1,0]
	v_pk_mul_f32 v[50:51], v[50:51], v[184:185] op_sel_hi:[1,0]
	v_pk_mul_f32 v[48:49], v[48:49], v[184:185] op_sel_hi:[1,0]
	v_pk_mul_f32 v[42:43], v[42:43], v[184:185] op_sel_hi:[1,0]
	v_pk_mul_f32 v[40:41], v[40:41], v[184:185] op_sel_hi:[1,0]
	v_pk_mul_f32 v[34:35], v[34:35], v[184:185] op_sel_hi:[1,0]
	v_pk_mul_f32 v[32:33], v[32:33], v[184:185] op_sel_hi:[1,0]
.LBB0_1378:
	v_exp_f32_e32 v136, v136
	v_exp_f32_e32 v137, v137
	v_exp_f32_e32 v138, v138
	v_exp_f32_e32 v139, v139
	v_exp_f32_e32 v140, v140
	v_exp_f32_e32 v141, v141
	v_exp_f32_e32 v142, v142
	v_exp_f32_e32 v143, v143
	v_exp_f32_e32 v128, v128
	v_exp_f32_e32 v129, v129
	v_exp_f32_e32 v130, v130
	v_exp_f32_e32 v131, v131
	v_exp_f32_e32 v132, v132
	v_exp_f32_e32 v133, v133
	v_exp_f32_e32 v134, v134
	v_exp_f32_e32 v135, v135
	v_cvt_pk_bf16_f32 v136, v136, v137
	v_cvt_pk_bf16_f32 v137, v138, v139
	v_cvt_pk_bf16_f32 v138, v140, v141
	v_cvt_pk_bf16_f32 v139, v142, v143
	v_cvt_pk_bf16_f32 v128, v128, v129
	v_cvt_pk_bf16_f32 v129, v130, v131
	v_cvt_pk_bf16_f32 v130, v132, v133
	v_cvt_pk_bf16_f32 v131, v134, v135
	s_xor_b32 s43, s0, 1
	s_mul_i32 s46, s43, 0x3800
	v_lshlrev_b32_e32 v244, 1, v170
	v_add3_u32 v244, s46, v244, v180
	v_lshlrev_b32_e32 v245, 1, v171
	v_add3_u32 v245, s46, v245, v144
	s_mulk_i32 s43, 0x2800
	v_add_u32_e32 v202, s43, v174
	s_waitcnt vmcnt(0)
	ds_write_b128 v244, v[72:75]
	s_and_saveexec_b64 s[100:101], s[6:7]
	ds_write_b128 v245, v[28:31]
	s_or_b64 exec, exec, s[100:101]
	ds_write_b128 v202, v[232:235] offset:28672
	s_waitcnt lgkmcnt(0)
	s_barrier
	v_add_u32_e32 v244, s46, v175
	ds_read_b128 v[236:239], v244
	ds_read_b128 v[240:243], v244 offset:64
	v_mfma_f32_16x16x32_bf16 v[60:63], v[112:115], v[136:139], v[60:63]
	v_exp_f32_e32 v116, v116
	v_mfma_f32_16x16x32_bf16 v[56:59], v[112:115], v[128:131], v[56:59]
	v_exp_f32_e32 v112, v117
	v_exp_f32_e32 v113, v118
	v_exp_f32_e32 v114, v119
	v_exp_f32_e32 v115, v120
	v_exp_f32_e32 v117, v121
	v_mfma_f32_16x16x32_bf16 v[52:55], v[108:111], v[136:139], v[52:55]
	v_exp_f32_e32 v118, v122
	v_mfma_f32_16x16x32_bf16 v[48:51], v[108:111], v[128:131], v[48:51]
	v_cvt_pk_bf16_f32 v108, v116, v112
	v_cvt_pk_bf16_f32 v109, v113, v114
	v_cvt_pk_bf16_f32 v110, v115, v117
	v_exp_f32_e32 v111, v123
	v_mfma_f32_16x16x32_bf16 v[44:47], v[96:99], v[136:139], v[44:47]
	v_cvt_pk_bf16_f32 v111, v118, v111
	v_mfma_f32_16x16x32_bf16 v[40:43], v[96:99], v[128:131], v[40:43]
	v_exp_f32_e32 v96, v100
	v_exp_f32_e32 v97, v101
	v_exp_f32_e32 v98, v102
	v_exp_f32_e32 v99, v103
	v_exp_f32_e32 v100, v104
	v_exp_f32_e32 v101, v105
	v_exp_f32_e32 v102, v106
	v_exp_f32_e32 v103, v107
	v_mfma_f32_16x16x32_bf16 v[68:71], v[124:127], v[136:139], v[68:71]
	v_cvt_pk_bf16_f32 v96, v96, v97
	v_cvt_pk_bf16_f32 v97, v98, v99
	v_cvt_pk_bf16_f32 v98, v100, v101
	v_mfma_f32_16x16x32_bf16 v[64:67], v[124:127], v[128:131], v[64:67]
	v_cvt_pk_bf16_f32 v99, v102, v103
	v_mfma_f32_16x16x32_bf16 v[36:39], v[228:231], v[136:139], v[36:39]
	v_mfma_f32_16x16x32_bf16 v[32:35], v[228:231], v[128:131], v[32:35]
	v_mfma_f32_16x16x32_bf16 v[68:71], v[92:95], v[108:111], v[68:71]
	v_mfma_f32_16x16x32_bf16 v[64:67], v[92:95], v[96:99], v[64:67]
	v_mfma_f32_16x16x32_bf16 v[60:63], v[88:91], v[108:111], v[60:63]
	v_mfma_f32_16x16x32_bf16 v[56:59], v[88:91], v[96:99], v[56:59]
	v_mfma_f32_16x16x32_bf16 v[52:55], v[84:87], v[108:111], v[52:55]
	v_mfma_f32_16x16x32_bf16 v[48:51], v[84:87], v[96:99], v[48:51]
	v_mfma_f32_16x16x32_bf16 v[44:47], v[80:83], v[108:111], v[44:47]
	v_mfma_f32_16x16x32_bf16 v[40:43], v[80:83], v[96:99], v[40:43]
	v_mfma_f32_16x16x32_bf16 v[36:39], v[228:231], v[108:111], v[36:39]
	v_mfma_f32_16x16x32_bf16 v[32:35], v[228:231], v[96:99], v[32:35]
	s_add_i32 s27, s27, 1
	s_cmp_lg_u32 s27, 35
	s_cbranch_scc1 .LBB0_1374
